# P1 in-projection GEMM epilogue: plain stores instead of sc1 write-through (store acks at L2, write-back overlaps the next tile)
# speedup vs baseline: 1.0079x; 1.0079x over previous
; __device__ __forceinline__ unsigned pk2_(float lo, float hi) { f32x2_t v = {lo, hi}; bf16x2_t b = __builtin_convertvector(v, bf16x2_t); return __builtin_bit_cast(unsigned, b); }
; __device__ __forceinline__ float sigm(float x) { return __builtin_amdgcn_rcpf(1.0f + __expf(-x)); }
; __device__ __forceinline__ float sigm(float x) { return __builtin_amdgcn_rcpf(1.0f + __expf(-x)); }
; __device__ __forceinline__ void store8_wt(void* p, u32x2w v) { asm volatile("global_store_dwordx2 %0, %1, off sc1\n\ts_nop 1" :: "v"(p), "v"(v) : "memory"); }
; __device__ __forceinline__ void store16_wt(void* p, u32x4 v) { asm volatile("global_store_dwordx4 %0, %1, off sc1\n\ts_nop 1" :: "v"(p), "v"(v) : "memory"); }
;     __device__ __forceinline__ void operator()(const f32x4 (&acc)[2][2][4][2], const Unit& u, int wr, int wc, int fr, int fq) const {
;     ...
;             for (int m = 0; m < 4; ++m) { bf16_t* rowp = O + (size_t)(row0 + ai * HALF + m * 16) * ldc + col0;
; #pragma unroll
;                 for (int bj = 0; bj < 2; ++bj) { f32x4 v0 = acc[ai][bj][m][0], v1 = acc[ai][bj][m][1];
;                     if (ACT == 1) { v0 = (f32x4){sigm(v0[0]), sigm(v0[1]), sigm(v0[2]), sigm(v0[3])}; v1 = (f32x4){sigm(v1[0]), sigm(v1[1]), sigm(v1[2]), sigm(v1[3])}; }
;                     u32x4 w; w.x = pk2_(v0[0], v0[1]); w.y = pk2_(v0[2], v0[3]); w.z = pk2_(v1[0], v1[1]); w.w = pk2_(v1[2], v1[3]);
;                     store16_wt(rowp + bj * HALF, w); } }
.LBB0_226:
	v_lshl_or_b32 v148, s30, 8, v153
	v_lshl_add_u32 v155, s29, 8, v17
	v_ashrrev_i32_e32 v149, 31, v148
	v_mad_i64_i32 v[150:151], s[12:13], v155, s34, v[140:141]
	v_lshlrev_b64 v[148:149], 1, v[148:149]
	v_lshl_add_u64 v[150:151], v[150:151], 0, v[148:149]
	v_cvt_pk_bf16_f32 v126, v126, v127
	v_cvt_pk_bf16_f32 v127, v128, v129
	v_cvt_pk_bf16_f32 v128, v122, v123
	v_cvt_pk_bf16_f32 v129, v124, v125
	global_store_dwordx4 v[150:151], v[126:129], off
	s_nop 1
	v_cvt_pk_bf16_f32 v110, v110, v111
	v_cvt_pk_bf16_f32 v111, v112, v113
	v_cvt_pk_bf16_f32 v112, v106, v107
	v_lshl_add_u64 v[106:107], v[150:151], 0, s[64:65]
	v_cvt_pk_bf16_f32 v113, v108, v109
	global_store_dwordx4 v[106:107], v[110:113], off
	s_nop 1
	v_or_b32_e32 v106, 16, v155
	v_mad_i64_i32 v[106:107], s[12:13], v106, s34, v[140:141]
	v_lshl_add_u64 v[110:111], v[106:107], 0, v[148:149]
	v_cvt_pk_bf16_f32 v106, v118, v119
	v_cvt_pk_bf16_f32 v107, v120, v121
	v_cvt_pk_bf16_f32 v108, v114, v115
	v_cvt_pk_bf16_f32 v109, v116, v117
	global_store_dwordx4 v[110:111], v[106:109], off
	s_nop 1
	v_cvt_pk_bf16_f32 v94, v94, v95
	v_cvt_pk_bf16_f32 v95, v96, v97
	v_cvt_pk_bf16_f32 v96, v90, v91
	v_lshl_add_u64 v[90:91], v[110:111], 0, s[64:65]
	v_cvt_pk_bf16_f32 v97, v92, v93
	global_store_dwordx4 v[90:91], v[94:97], off
	s_nop 1
	v_or_b32_e32 v90, 32, v155
	v_mad_i64_i32 v[90:91], s[12:13], v90, s34, v[140:141]
	v_lshl_add_u64 v[94:95], v[90:91], 0, v[148:149]
	v_cvt_pk_bf16_f32 v90, v102, v103
	v_cvt_pk_bf16_f32 v91, v104, v105
	v_cvt_pk_bf16_f32 v92, v98, v99
	v_cvt_pk_bf16_f32 v93, v100, v101
	global_store_dwordx4 v[94:95], v[90:93], off
	s_nop 1
	v_cvt_pk_bf16_f32 v78, v78, v79
	v_cvt_pk_bf16_f32 v79, v80, v81
	v_cvt_pk_bf16_f32 v80, v74, v75
	v_lshl_add_u64 v[74:75], v[94:95], 0, s[64:65]
	v_cvt_pk_bf16_f32 v81, v76, v77
	global_store_dwordx4 v[74:75], v[78:81], off
	s_nop 1
	v_or_b32_e32 v74, 48, v155
	v_mad_i64_i32 v[74:75], s[12:13], v74, s34, v[140:141]
	v_lshl_add_u64 v[78:79], v[74:75], 0, v[148:149]
	v_cvt_pk_bf16_f32 v74, v86, v87
	v_cvt_pk_bf16_f32 v75, v88, v89
	v_cvt_pk_bf16_f32 v76, v82, v83
	v_cvt_pk_bf16_f32 v77, v84, v85
	global_store_dwordx4 v[78:79], v[74:77], off
	s_nop 1
	v_cvt_pk_bf16_f32 v70, v70, v71
	v_cvt_pk_bf16_f32 v71, v72, v73
	v_cvt_pk_bf16_f32 v72, v66, v67
	v_lshl_add_u64 v[66:67], v[78:79], 0, s[64:65]
	v_cvt_pk_bf16_f32 v73, v68, v69
	global_store_dwordx4 v[66:67], v[70:73], off
	s_nop 1
	v_add_u32_e32 v66, 0x80, v155
	v_mad_i64_i32 v[66:67], s[12:13], v66, s34, v[140:141]
	v_lshl_add_u64 v[66:67], v[66:67], 0, v[148:149]
	v_cvt_pk_bf16_f32 v62, v62, v63
	v_cvt_pk_bf16_f32 v63, v64, v65
	v_cvt_pk_bf16_f32 v64, v58, v59
	v_cvt_pk_bf16_f32 v65, v60, v61
	global_store_dwordx4 v[66:67], v[62:65], off
	s_nop 1
	v_cvt_pk_bf16_f32 v46, v46, v47
	v_cvt_pk_bf16_f32 v47, v48, v49
	v_cvt_pk_bf16_f32 v48, v42, v43
	v_lshl_add_u64 v[42:43], v[66:67], 0, s[64:65]
	v_cvt_pk_bf16_f32 v49, v44, v45
	global_store_dwordx4 v[42:43], v[46:49], off
	s_nop 1
	v_add_u32_e32 v42, 0x90, v155
	v_mad_i64_i32 v[42:43], s[12:13], v42, s34, v[140:141]
	v_lshl_add_u64 v[46:47], v[42:43], 0, v[148:149]
	v_cvt_pk_bf16_f32 v42, v54, v55
	v_cvt_pk_bf16_f32 v43, v56, v57
	v_cvt_pk_bf16_f32 v44, v50, v51
	v_cvt_pk_bf16_f32 v45, v52, v53
	global_store_dwordx4 v[46:47], v[42:45], off
	s_nop 1
	v_cvt_pk_bf16_f32 v30, v30, v31
	v_cvt_pk_bf16_f32 v31, v32, v33
	v_cvt_pk_bf16_f32 v32, v26, v27
	v_lshl_add_u64 v[26:27], v[46:47], 0, s[64:65]
	v_cvt_pk_bf16_f32 v33, v28, v29
	global_store_dwordx4 v[26:27], v[30:33], off
	s_nop 1
	v_add_u32_e32 v26, 0xa0, v155
	v_mad_i64_i32 v[26:27], s[12:13], v26, s34, v[140:141]
	v_lshl_add_u64 v[30:31], v[26:27], 0, v[148:149]
	v_cvt_pk_bf16_f32 v26, v38, v39
	v_cvt_pk_bf16_f32 v27, v40, v41
	v_cvt_pk_bf16_f32 v28, v34, v35
	v_cvt_pk_bf16_f32 v29, v36, v37
	global_store_dwordx4 v[30:31], v[26:29], off
	s_nop 1
	v_cvt_pk_bf16_f32 v12, v12, v13
	v_cvt_pk_bf16_f32 v13, v14, v15
	v_cvt_pk_bf16_f32 v14, v8, v9
	v_lshl_add_u64 v[8:9], v[30:31], 0, s[64:65]
	v_cvt_pk_bf16_f32 v15, v10, v11
	global_store_dwordx4 v[8:9], v[12:15], off
	s_nop 1
	v_add_u32_e32 v8, 0xb0, v155
	v_mad_i64_i32 v[8:9], s[12:13], v8, s34, v[140:141]
	v_lshl_add_u64 v[12:13], v[8:9], 0, v[148:149]
	v_cvt_pk_bf16_f32 v8, v22, v23
	v_cvt_pk_bf16_f32 v9, v24, v25
	v_cvt_pk_bf16_f32 v10, v18, v19
	v_cvt_pk_bf16_f32 v11, v20, v21
	global_store_dwordx4 v[12:13], v[8:11], off
	s_nop 1
	v_cvt_pk_bf16_f32 v4, v4, v5
	v_cvt_pk_bf16_f32 v5, v6, v7
	v_cvt_pk_bf16_f32 v6, v0, v1
	v_cvt_pk_bf16_f32 v7, v2, v3
	v_lshl_add_u64 v[0:1], v[12:13], 0, s[64:65]
	global_store_dwordx4 v[0:1], v[4:7], off
	s_nop 1
	s_andn2_b64 vcc, exec, s[36:37]
	s_mov_b64 s[12:13], -1
	s_cbranch_vccnz .LBB0_215
	s_andn2_b64 vcc, exec, s[4:5]
	s_cbranch_vccnz .LBB0_214
	s_barrier
	s_branch .LBB0_214
